# e32 lever 4 on the sample-attention loop: static s_setprio 2 for the loader waves (memory-critical role), on top of v71
# baseline (speedup 1.0000x reference)
; __device__ __forceinline__ void attn_sample_unit(int b, int h, int split, const bf16* __restrict__ Q, const float* __restrict__ cache_k, const float* __restrict__ cache_v, ...
;     ...
;     SL_LOAD(0); SL_WRITE(0); SL_LOAD(1);
.LBB0_368:
	s_and_b64 vcc, exec, s[18:19]
	s_cbranch_vccz .LBB0_354
	v_readfirstlane_b32 s5, v101
	s_ashr_i32 s20, s48, 4
	s_lshl_b32 s38, s5, 24
	s_lshl_b32 s5, s5, 19
	s_ashr_i32 s21, s20, 31
	s_or_b32 s42, s5, 0xf00000
	s_lshl_b64 s[6:7], s[20:21], 12
	s_lshl_b32 s5, s64, 11
	s_add_i32 s10, s36, -4
	s_or_b32 s5, s6, s5
	s_add_u32 s6, s5, s10
	s_addc_u32 s7, s7, 0
	s_lshl_b64 s[18:19], s[6:7], 13
	s_add_u32 s5, s44, s18
	s_addc_u32 s6, s45, s19
	s_lshl_b32 s40, s4, 2
	s_add_u32 s4, s5, s40
	s_addc_u32 s5, s6, 0
	s_add_u32 s6, s46, s18
	s_addc_u32 s7, s47, s19
	s_add_u32 s6, s6, s40
	s_addc_u32 s7, s7, 0
	global_load_dwordx4 v[108:111], v100, s[4:5] nt
	global_load_dwordx4 v[112:115], v100, s[6:7] nt
	v_mov_b32_e32 v101, v3
	v_lshl_add_u64 v[4:5], s[4:5], 0, v[100:101]
	v_lshl_add_u64 v[6:7], s[6:7], 0, v[100:101]
	v_lshl_add_u64 v[4:5], v[4:5], 0, s[72:73]
	v_lshl_add_u64 v[6:7], v[6:7], 0, s[72:73]
	flat_load_dwordx4 v[116:119], v[4:5] nt
	flat_load_dwordx4 v[120:123], v[6:7] nt
	v_lshl_add_u64 v[4:5], v[4:5], 0, s[72:73]
	v_lshl_add_u64 v[6:7], v[6:7], 0, s[72:73]
	flat_load_dwordx4 v[124:127], v[4:5] nt
	flat_load_dwordx4 v[128:131], v[6:7] nt
	v_lshl_add_u64 v[4:5], v[4:5], 0, s[72:73]
	v_lshl_add_u64 v[6:7], v[6:7], 0, s[72:73]
	flat_load_dwordx4 v[148:151], v[4:5] nt
	flat_load_dwordx4 v[152:155], v[6:7] nt
	v_lshl_add_u64 v[4:5], v[4:5], 0, s[72:73]
	v_lshl_add_u64 v[6:7], v[6:7], 0, s[72:73]
	flat_load_dwordx4 v[172:175], v[4:5] nt
	flat_load_dwordx4 v[92:95], v[6:7] nt
	v_lshl_add_u64 v[4:5], v[4:5], 0, s[72:73]
	v_lshl_add_u64 v[6:7], v[6:7], 0, s[72:73]
	flat_load_dwordx4 v[88:91], v[4:5] nt
	flat_load_dwordx4 v[84:87], v[6:7] nt
	v_lshl_add_u64 v[4:5], v[4:5], 0, s[72:73]
	v_lshl_add_u64 v[6:7], v[6:7], 0, s[72:73]
	flat_load_dwordx4 v[80:83], v[4:5] nt
	flat_load_dwordx4 v[76:79], v[6:7] nt
	v_lshl_add_u64 v[4:5], v[4:5], 0, s[72:73]
	v_lshl_add_u64 v[6:7], v[6:7], 0, s[72:73]
	flat_load_dwordx4 v[72:75], v[4:5] nt
	flat_load_dwordx4 v[68:71], v[6:7] nt
	v_lshl_add_u64 v[4:5], v[4:5], 0, s[72:73]
	v_lshl_add_u64 v[6:7], v[6:7], 0, s[72:73]
	flat_load_dwordx4 v[64:67], v[4:5] nt
	flat_load_dwordx4 v[60:63], v[6:7] nt
	v_lshl_add_u64 v[4:5], v[4:5], 0, s[72:73]
	v_lshl_add_u64 v[6:7], v[6:7], 0, s[72:73]
	flat_load_dwordx4 v[56:59], v[4:5] nt
	flat_load_dwordx4 v[52:55], v[6:7] nt
	v_lshl_add_u64 v[4:5], v[4:5], 0, s[72:73]
	v_lshl_add_u64 v[6:7], v[6:7], 0, s[72:73]
	flat_load_dwordx4 v[48:51], v[4:5] nt
	flat_load_dwordx4 v[44:47], v[6:7] nt
	v_lshl_add_u64 v[4:5], v[4:5], 0, s[72:73]
	v_lshl_add_u64 v[6:7], v[6:7], 0, s[72:73]
	flat_load_dwordx4 v[40:43], v[4:5] nt
	flat_load_dwordx4 v[36:39], v[6:7] nt
	v_lshl_add_u64 v[4:5], v[4:5], 0, s[72:73]
	v_lshl_add_u64 v[6:7], v[6:7], 0, s[72:73]
	flat_load_dwordx4 v[32:35], v[4:5] nt
	flat_load_dwordx4 v[28:31], v[6:7] nt
	v_lshl_add_u64 v[4:5], v[4:5], 0, s[72:73]
	v_lshl_add_u64 v[6:7], v[6:7], 0, s[72:73]
	flat_load_dwordx4 v[24:27], v[4:5] nt
	flat_load_dwordx4 v[20:23], v[6:7] nt
	v_lshl_add_u64 v[4:5], v[4:5], 0, s[72:73]
	v_lshl_add_u64 v[6:7], v[6:7], 0, s[72:73]
	flat_load_dwordx4 v[16:19], v[4:5] nt
	flat_load_dwordx4 v[12:15], v[6:7] nt
	v_lshl_add_u64 v[96:97], v[4:5], 0, s[72:73]
	v_lshl_add_u64 v[98:99], v[6:7], 0, s[72:73]
	flat_load_dwordx4 v[8:11], v[96:97] nt
	flat_load_dwordx4 v[4:7], v[98:99] nt
	v_lshl_add_u64 v[96:97], v[96:97], 0, s[72:73]
	v_lshl_add_u64 v[98:99], v[98:99], 0, s[72:73]
	v_lshlrev_b32_e32 v2, 3, v106
	v_lshlrev_b32_e32 v139, 14, v107
	v_and_b32_e32 v98, 0xf0, v2
	s_lshl_b32 s5, s10, 4
	s_lshl_b32 s6, s10, 1
	v_add_u32_e32 v97, 0, v139
	s_lshl_b32 s43, s10, 8
	v_bitop3_b32 v141, s5, v98, v202 bitop3:0x6c
	s_and_b32 s5, s10, 0xfffff0
	s_and_b32 s6, s6, 8
	v_and_b32_e32 v138, 8, v2
	v_add_u32_e32 v99, s43, v97
	s_or_b32 s5, s6, s5
	s_lshr_b32 s6, s10, 1
	v_lshlrev_b32_e32 v2, 9, v132
	v_bfe_u32 v96, v104, 3, 2
	s_bfe_u32 s4, s37, 0x20006
	v_add3_u32 v99, v99, v141, v138
	s_and_b32 s6, s6, 4
	s_lshr_b32 s5, s5, 1
	v_and_b32_e32 v140, 0x4000, v2
	s_waitcnt vmcnt(0)
	v_cvt_pk_bf16_f32 v102, v108, v109
	v_cvt_pk_bf16_f32 v103, v110, v111
	ds_write_b64 v99, v[102:103]
	v_or_b32_e32 v99, s5, v96
	s_or_b32 s5, s6, s4
	v_add_u32_e32 v2, 0, v140
	v_lshlrev_b32_e32 v142, 9, v99
	s_lshl_b32 s65, s5, 6
	v_and_b32_e32 v136, 48, v105
	v_and_b32_e32 v137, 8, v105
	v_add3_u32 v99, v2, v142, s65
	s_lshl_b32 s5, s36, 4
	s_lshl_b32 s6, s36, 1
	v_add3_u32 v99, v99, v136, v137
	s_lshl_b32 s66, s36, 8
	v_bitop3_b32 v143, s5, v98, v202 bitop3:0x6c
	s_and_b32 s5, s36, 0xfffff0
	s_and_b32 s6, s6, 8
	v_cvt_pk_bf16_f32 v102, v112, v113
	v_cvt_pk_bf16_f32 v103, v114, v115
	ds_write_b64 v99, v[102:103] offset:32768
	v_add_u32_e32 v99, s66, v97
	s_or_b32 s5, s6, s5
	s_lshr_b32 s6, s36, 1
	v_add3_u32 v99, v99, v143, v138
	s_and_b32 s6, s6, 4
	s_lshr_b32 s5, s5, 1
	s_waitcnt lgkmcnt(0)
	v_cvt_pk_bf16_f32 v102, v116, v117
	v_cvt_pk_bf16_f32 v103, v118, v119
	ds_write_b64 v99, v[102:103]
	v_or_b32_e32 v99, s5, v96
	s_or_b32 s5, s6, s4
	v_lshlrev_b32_e32 v144, 9, v99
	s_lshl_b32 s41, s5, 6
	s_add_i32 s5, s36, 4
	v_add3_u32 v99, v2, v144, s41
	s_lshl_b32 s6, s5, 4
	s_lshl_b32 s7, s5, 1
	v_add3_u32 v99, v99, v136, v137
	s_lshl_b32 s67, s5, 8
	v_bitop3_b32 v145, s6, v98, v202 bitop3:0x6c
	s_and_b32 s6, s5, 0xfffff0
	s_and_b32 s7, s7, 8
	v_cvt_pk_bf16_f32 v102, v120, v121
	v_cvt_pk_bf16_f32 v103, v122, v123
	ds_write_b64 v99, v[102:103] offset:32768
	v_add_u32_e32 v99, s67, v97
	s_or_b32 s6, s7, s6
	s_lshr_b32 s5, s5, 1
	v_add3_u32 v99, v99, v145, v138
	s_and_b32 s5, s5, 4
	s_lshr_b32 s6, s6, 1
	v_cvt_pk_bf16_f32 v102, v124, v125
	v_cvt_pk_bf16_f32 v103, v126, v127
	ds_write_b64 v99, v[102:103]
	v_or_b32_e32 v99, s6, v96
	s_or_b32 s5, s5, s4
	v_lshlrev_b32_e32 v146, 9, v99
	s_lshl_b32 s77, s5, 6
	s_add_i32 s5, s36, 8
	v_add3_u32 v99, v2, v146, s77
	s_lshl_b32 s6, s5, 4
	s_lshl_b32 s7, s5, 1
	v_add3_u32 v99, v99, v136, v137
	s_lshl_b32 s78, s5, 8
	v_bitop3_b32 v147, s6, v98, v202 bitop3:0x6c
	s_and_b32 s6, s5, 0xfffff0
	s_and_b32 s7, s7, 8
	v_cvt_pk_bf16_f32 v102, v128, v129
	v_cvt_pk_bf16_f32 v103, v130, v131
	ds_write_b64 v99, v[102:103] offset:32768
	v_add_u32_e32 v99, s78, v97
	s_or_b32 s6, s7, s6
	s_lshr_b32 s5, s5, 1
	v_add3_u32 v99, v99, v147, v138
	s_and_b32 s5, s5, 4
	s_lshr_b32 s6, s6, 1
	v_cvt_pk_bf16_f32 v102, v148, v149
	v_cvt_pk_bf16_f32 v103, v150, v151
	ds_write_b64 v99, v[102:103]
	v_or_b32_e32 v99, s6, v96
	s_or_b32 s5, s5, s4
	v_lshlrev_b32_e32 v148, 9, v99
	s_lshl_b32 s79, s5, 6
	s_add_i32 s5, s36, 12
	v_add3_u32 v99, v2, v148, s79
	s_lshl_b32 s6, s5, 4
	s_lshl_b32 s7, s5, 1
	v_add3_u32 v99, v99, v136, v137
	s_lshl_b32 s80, s5, 8
	v_bitop3_b32 v149, s6, v98, v202 bitop3:0x6c
	s_and_b32 s6, s5, 0xfffff0
	s_and_b32 s7, s7, 8
	s_lshr_b32 s5, s5, 1
	v_cvt_pk_bf16_f32 v102, v152, v153
	v_cvt_pk_bf16_f32 v103, v154, v155
	ds_write_b64 v99, v[102:103] offset:32768
	v_add_u32_e32 v99, s80, v97
	s_or_b32 s6, s7, s6
	s_and_b32 s5, s5, 4
	v_add3_u32 v99, v99, v149, v138
	s_lshr_b32 s6, s6, 1
	s_or_b32 s5, s5, s4
	v_cvt_pk_bf16_f32 v102, v172, v173
	v_cvt_pk_bf16_f32 v103, v174, v175
	ds_write_b64 v99, v[102:103]
	v_cvt_pk_bf16_f32 v92, v92, v93
	v_cvt_pk_bf16_f32 v93, v94, v95
	v_or_b32_e32 v94, s6, v96
	s_lshl_b32 s81, s5, 6
	s_add_i32 s5, s36, 16
	v_lshlrev_b32_e32 v150, 9, v94
	s_lshl_b32 s6, s5, 4
	v_add3_u32 v94, v2, v150, s81
	s_lshl_b32 s82, s5, 8
	v_bitop3_b32 v151, s6, v98, v202 bitop3:0x6c
	s_and_b32 s6, s5, 0xfffff0
	s_lshl_b32 s5, s5, 1
	v_add3_u32 v94, v94, v136, v137
	s_and_b32 s5, s5, 8
	ds_write_b64 v94, v[92:93] offset:32768
	v_cvt_pk_bf16_f32 v88, v88, v89
	v_cvt_pk_bf16_f32 v89, v90, v91
	v_add_u32_e32 v90, s82, v97
	s_or_b32 s5, s5, s6
	v_add3_u32 v90, v90, v151, v138
	s_lshr_b32 s5, s5, 1
	ds_write_b64 v90, v[88:89]
	v_cvt_pk_bf16_f32 v84, v84, v85
	v_cvt_pk_bf16_f32 v85, v86, v87
	v_or_b32_e32 v86, s5, v96
	v_lshlrev_b32_e32 v152, 9, v86
	s_add_i32 s5, s36, 20
	v_add3_u32 v86, v2, v152, s41
	s_lshl_b32 s6, s5, 4
	s_lshl_b32 s7, s5, 1
	v_add3_u32 v86, v86, v136, v137
	s_lshl_b32 s83, s5, 8
	v_bitop3_b32 v153, s6, v98, v202 bitop3:0x6c
	s_and_b32 s6, s5, 0xfffff0
	s_and_b32 s7, s7, 8
	ds_write_b64 v86, v[84:85] offset:32768
	v_cvt_pk_bf16_f32 v80, v80, v81
	v_cvt_pk_bf16_f32 v81, v82, v83
	v_add_u32_e32 v82, s83, v97
	s_or_b32 s6, s7, s6
	s_lshr_b32 s5, s5, 1
	v_add3_u32 v82, v82, v153, v138
	s_and_b32 s5, s5, 4
	s_lshr_b32 s6, s6, 1
	ds_write_b64 v82, v[80:81]
	v_cvt_pk_bf16_f32 v76, v76, v77
	v_cvt_pk_bf16_f32 v77, v78, v79
	v_or_b32_e32 v78, s6, v96
	s_or_b32 s5, s5, s4
	v_lshlrev_b32_e32 v154, 9, v78
	s_lshl_b32 s84, s5, 6
	s_add_i32 s5, s36, 24
	v_add3_u32 v78, v2, v154, s84
	s_lshl_b32 s6, s5, 4
	s_lshl_b32 s7, s5, 1
	v_add3_u32 v78, v78, v136, v137
	s_lshl_b32 s85, s5, 8
	v_bitop3_b32 v155, s6, v98, v202 bitop3:0x6c
	s_and_b32 s6, s5, 0xfffff0
	s_and_b32 s7, s7, 8
	ds_write_b64 v78, v[76:77] offset:32768
	v_cvt_pk_bf16_f32 v72, v72, v73
	v_cvt_pk_bf16_f32 v73, v74, v75
	v_add_u32_e32 v74, s85, v97
	s_or_b32 s6, s7, s6
	s_lshr_b32 s5, s5, 1
	v_add3_u32 v74, v74, v155, v138
	s_and_b32 s5, s5, 4
	s_lshr_b32 s6, s6, 1
	ds_write_b64 v74, v[72:73]
	v_cvt_pk_bf16_f32 v68, v68, v69
	v_cvt_pk_bf16_f32 v69, v70, v71
	v_or_b32_e32 v70, s6, v96
	s_or_b32 s5, s5, s4
	v_lshlrev_b32_e32 v172, 9, v70
	s_lshl_b32 s86, s5, 6
	s_add_i32 s5, s36, 28
	v_add3_u32 v70, v2, v172, s86
	s_lshl_b32 s6, s5, 4
	s_lshl_b32 s7, s5, 1
	v_add3_u32 v70, v70, v136, v137
	s_lshl_b32 s87, s5, 8
	v_bitop3_b32 v173, s6, v98, v202 bitop3:0x6c
	s_and_b32 s6, s5, 0xfffff0
	s_and_b32 s7, s7, 8
	s_lshr_b32 s5, s5, 1
	ds_write_b64 v70, v[68:69] offset:32768
	v_cvt_pk_bf16_f32 v64, v64, v65
	v_cvt_pk_bf16_f32 v65, v66, v67
	v_add_u32_e32 v66, s87, v97
	s_or_b32 s6, s7, s6
	s_and_b32 s5, s5, 4
	v_add3_u32 v66, v66, v173, v138
	s_lshr_b32 s6, s6, 1
	s_or_b32 s5, s5, s4
	ds_write_b64 v66, v[64:65]
	v_cvt_pk_bf16_f32 v60, v60, v61
	v_cvt_pk_bf16_f32 v61, v62, v63
	v_or_b32_e32 v62, s6, v96
	s_lshl_b32 s88, s5, 6
	s_add_i32 s5, s36, 32
	v_lshlrev_b32_e32 v174, 9, v62
	s_lshl_b32 s6, s5, 4
	v_add3_u32 v62, v2, v174, s88
	s_lshl_b32 s89, s5, 8
	v_bitop3_b32 v175, s6, v98, v202 bitop3:0x6c
	s_and_b32 s6, s5, 0xfffff0
	s_lshl_b32 s5, s5, 1
	v_add3_u32 v62, v62, v136, v137
	s_and_b32 s5, s5, 8
	ds_write_b64 v62, v[60:61] offset:32768
	v_cvt_pk_bf16_f32 v56, v56, v57
	v_cvt_pk_bf16_f32 v57, v58, v59
	v_add_u32_e32 v58, s89, v97
	s_or_b32 s5, s5, s6
	v_add3_u32 v58, v58, v175, v138
	s_lshr_b32 s5, s5, 1
	ds_write_b64 v58, v[56:57]
	v_cvt_pk_bf16_f32 v52, v52, v53
	v_cvt_pk_bf16_f32 v53, v54, v55
	v_or_b32_e32 v54, s5, v96
	v_lshlrev_b32_e32 v176, 9, v54
	s_add_i32 s5, s36, 36
	v_add3_u32 v54, v2, v176, s41
	s_lshl_b32 s6, s5, 4
	s_lshl_b32 s7, s5, 1
	v_add3_u32 v54, v54, v136, v137
	s_lshl_b32 s90, s5, 8
	v_bitop3_b32 v177, s6, v98, v202 bitop3:0x6c
	s_and_b32 s6, s5, 0xfffff0
	s_and_b32 s7, s7, 8
	ds_write_b64 v54, v[52:53] offset:32768
	v_cvt_pk_bf16_f32 v48, v48, v49
	v_cvt_pk_bf16_f32 v49, v50, v51
	v_add_u32_e32 v50, s90, v97
	s_or_b32 s6, s7, s6
	s_lshr_b32 s5, s5, 1
	v_add3_u32 v50, v50, v177, v138
	s_and_b32 s5, s5, 4
	s_lshr_b32 s6, s6, 1
	ds_write_b64 v50, v[48:49]
	v_cvt_pk_bf16_f32 v44, v44, v45
	v_cvt_pk_bf16_f32 v45, v46, v47
	v_or_b32_e32 v46, s6, v96
	s_or_b32 s5, s5, s4
	v_lshlrev_b32_e32 v178, 9, v46
	s_lshl_b32 s91, s5, 6
	s_add_i32 s5, s36, 40
	v_add3_u32 v46, v2, v178, s91
	s_lshl_b32 s6, s5, 4
	s_lshl_b32 s7, s5, 1
	v_add3_u32 v46, v46, v136, v137
	s_lshl_b32 s92, s5, 8
	v_bitop3_b32 v179, s6, v98, v202 bitop3:0x6c
	s_and_b32 s6, s5, 0xfffff0
	s_and_b32 s7, s7, 8
	ds_write_b64 v46, v[44:45] offset:32768
	v_cvt_pk_bf16_f32 v40, v40, v41
	v_cvt_pk_bf16_f32 v41, v42, v43
	v_add_u32_e32 v42, s92, v97
	s_or_b32 s6, s7, s6
	s_lshr_b32 s5, s5, 1
	v_add3_u32 v42, v42, v179, v138
	s_and_b32 s5, s5, 4
	s_lshr_b32 s6, s6, 1
	ds_write_b64 v42, v[40:41]
	v_cvt_pk_bf16_f32 v36, v36, v37
	v_cvt_pk_bf16_f32 v37, v38, v39
	v_or_b32_e32 v38, s6, v96
	s_or_b32 s5, s5, s4
	s_mov_b32 s34, s93
	v_lshlrev_b32_e32 v180, 9, v38
	s_lshl_b32 s93, s5, 6
	s_add_i32 s5, s36, 44
	v_add3_u32 v38, v2, v180, s93
	s_lshl_b32 s6, s5, 4
	s_lshl_b32 s7, s5, 1
	s_mov_b64 s[26:27], s[94:95]
	v_add3_u32 v38, v38, v136, v137
	s_lshl_b32 s94, s5, 8
	v_bitop3_b32 v181, s6, v98, v202 bitop3:0x6c
	s_and_b32 s6, s5, 0xfffff0
	s_and_b32 s7, s7, 8
	s_lshr_b32 s5, s5, 1
	ds_write_b64 v38, v[36:37] offset:32768
	v_cvt_pk_bf16_f32 v32, v32, v33
	v_cvt_pk_bf16_f32 v33, v34, v35
	v_add_u32_e32 v34, s94, v97
	s_or_b32 s6, s7, s6
	s_and_b32 s5, s5, 4
	v_add3_u32 v34, v34, v181, v138
	s_lshr_b32 s6, s6, 1
	s_or_b32 s5, s5, s4
	ds_write_b64 v34, v[32:33]
	v_cvt_pk_bf16_f32 v28, v28, v29
	v_cvt_pk_bf16_f32 v29, v30, v31
	v_or_b32_e32 v30, s6, v96
	s_lshl_b32 s95, s5, 6
	s_add_i32 s5, s36, 48
	v_lshlrev_b32_e32 v182, 9, v30
	s_lshl_b32 s6, s5, 4
	s_mov_b32 s75, s96
	v_add3_u32 v30, v2, v182, s95
	s_lshl_b32 s96, s5, 8
	v_bitop3_b32 v183, s6, v98, v202 bitop3:0x6c
	s_and_b32 s6, s5, 0xfffff0
	s_lshl_b32 s5, s5, 1
	v_add3_u32 v30, v30, v136, v137
	s_and_b32 s5, s5, 8
	ds_write_b64 v30, v[28:29] offset:32768
	v_cvt_pk_bf16_f32 v24, v24, v25
	v_cvt_pk_bf16_f32 v25, v26, v27
	v_add_u32_e32 v26, s96, v97
	s_or_b32 s5, s5, s6
	v_add3_u32 v26, v26, v183, v138
	s_lshr_b32 s5, s5, 1
	ds_write_b64 v26, v[24:25]
	v_cvt_pk_bf16_f32 v20, v20, v21
	v_cvt_pk_bf16_f32 v21, v22, v23
	v_or_b32_e32 v22, s5, v96
	v_lshlrev_b32_e32 v184, 9, v22
	s_add_i32 s5, s36, 52
	v_add3_u32 v22, v2, v184, s41
	s_lshl_b32 s6, s5, 4
	s_lshl_b32 s7, s5, 1
	v_add3_u32 v22, v22, v136, v137
	s_lshl_b32 s97, s5, 8
	v_bitop3_b32 v185, s6, v98, v202 bitop3:0x6c
	s_and_b32 s6, s5, 0xfffff0
	s_and_b32 s7, s7, 8
	s_lshr_b32 s5, s5, 1
	ds_write_b64 v22, v[20:21] offset:32768
	v_cvt_pk_bf16_f32 v16, v16, v17
	v_cvt_pk_bf16_f32 v17, v18, v19
	v_add_u32_e32 v18, s97, v97
	s_or_b32 s6, s7, s6
	s_and_b32 s5, s5, 4
	v_add3_u32 v18, v18, v185, v138
	s_lshr_b32 s6, s6, 1
	s_or_b32 s5, s5, s4
	s_add_i32 s36, s36, 56
	ds_write_b64 v18, v[16:17]
	v_cvt_pk_bf16_f32 v12, v12, v13
	v_cvt_pk_bf16_f32 v13, v14, v15
	v_or_b32_e32 v14, s6, v96
	s_lshl_b32 s70, s5, 6
	s_lshl_b32 s5, s36, 4
	s_lshl_b32 s6, s36, 1
	v_lshlrev_b32_e32 v186, 9, v14
	v_bitop3_b32 v187, s5, v98, v202 bitop3:0x6c
	s_and_b32 s5, s36, 0xfffff0
	s_and_b32 s6, s6, 8
	v_add3_u32 v14, v2, v186, s70
	s_or_b32 s5, s6, s5
	s_lshr_b32 s6, s36, 1
	v_add3_u32 v14, v14, v136, v137
	s_lshl_b32 s71, s36, 8
	s_and_b32 s6, s6, 4
	ds_write_b64 v14, v[12:13] offset:32768
	v_cvt_pk_bf16_f32 v8, v8, v9
	v_cvt_pk_bf16_f32 v9, v10, v11
	v_add_u32_e32 v10, s71, v97
	s_or_b32 s4, s6, s4
	v_add3_u32 v10, v10, v187, v138
; __device__ __forceinline__ void attn_sample_unit(int b, int h, int split, const bf16* __restrict__ Q, const float* __restrict__ cache_k, const float* __restrict__ cache_v, ...
;     ...
;     SL_LOAD(0); SL_WRITE(0); SL_LOAD(1);
;     __syncthreads();
	s_lshr_b32 s5, s5, 1
	s_lshl_b32 s4, s4, 6
	ds_write_b64 v10, v[8:9]
	v_cvt_pk_bf16_f32 v4, v4, v5
	v_cvt_pk_bf16_f32 v5, v6, v7
	v_or_b32_e32 v6, s5, v96
	s_add_u32 s5, s18, 0x80000
	s_addc_u32 s8, s19, 0
	s_add_u32 s6, s44, s5
	s_addc_u32 s7, s45, s8
	s_add_u32 s6, s6, s40
	s_addc_u32 s7, s7, 0
	s_add_u32 s5, s46, s5
	v_lshlrev_b32_e32 v188, 9, v6
	s_addc_u32 s9, s47, s8
	v_add3_u32 v2, v2, v188, s4
	s_add_u32 s8, s5, s40
	v_add3_u32 v2, v2, v136, v137
	s_addc_u32 s9, s9, 0
	ds_write_b64 v2, v[4:5] offset:32768
	v_lshl_add_u64 v[4:5], s[6:7], 0, v[100:101]
	v_lshl_add_u64 v[6:7], s[8:9], 0, v[100:101]
	v_lshl_add_u64 v[4:5], v[4:5], 0, s[72:73]
	v_lshl_add_u64 v[6:7], v[6:7], 0, s[72:73]
	global_load_dwordx4 v[128:131], v100, s[6:7] nt
	global_load_dwordx4 v[124:127], v100, s[8:9] nt
	flat_load_dwordx4 v[120:123], v[4:5] nt
	flat_load_dwordx4 v[116:119], v[6:7] nt
	v_lshl_add_u64 v[4:5], v[4:5], 0, s[72:73]
	v_lshl_add_u64 v[6:7], v[6:7], 0, s[72:73]
	flat_load_dwordx4 v[112:115], v[4:5] nt
	flat_load_dwordx4 v[108:111], v[6:7] nt
	v_lshl_add_u64 v[4:5], v[4:5], 0, s[72:73]
	v_lshl_add_u64 v[6:7], v[6:7], 0, s[72:73]
	flat_load_dwordx4 v[104:107], v[4:5] nt
	flat_load_dwordx4 v[100:103], v[6:7] nt
	v_lshl_add_u64 v[4:5], v[4:5], 0, s[72:73]
	v_lshl_add_u64 v[6:7], v[6:7], 0, s[72:73]
	flat_load_dwordx4 v[96:99], v[4:5] nt
	flat_load_dwordx4 v[88:91], v[6:7] nt
	v_lshl_add_u64 v[4:5], v[4:5], 0, s[72:73]
	v_lshl_add_u64 v[6:7], v[6:7], 0, s[72:73]
	flat_load_dwordx4 v[92:95], v[4:5] nt
	flat_load_dwordx4 v[80:83], v[6:7] nt
	v_lshl_add_u64 v[4:5], v[4:5], 0, s[72:73]
	v_lshl_add_u64 v[6:7], v[6:7], 0, s[72:73]
	flat_load_dwordx4 v[84:87], v[4:5] nt
	flat_load_dwordx4 v[72:75], v[6:7] nt
	v_lshl_add_u64 v[4:5], v[4:5], 0, s[72:73]
	v_lshl_add_u64 v[6:7], v[6:7], 0, s[72:73]
	flat_load_dwordx4 v[76:79], v[4:5] nt
	flat_load_dwordx4 v[64:67], v[6:7] nt
	v_lshl_add_u64 v[4:5], v[4:5], 0, s[72:73]
	v_lshl_add_u64 v[6:7], v[6:7], 0, s[72:73]
	flat_load_dwordx4 v[68:71], v[4:5] nt
	flat_load_dwordx4 v[56:59], v[6:7] nt
	v_lshl_add_u64 v[4:5], v[4:5], 0, s[72:73]
	v_lshl_add_u64 v[6:7], v[6:7], 0, s[72:73]
	flat_load_dwordx4 v[60:63], v[4:5] nt
	flat_load_dwordx4 v[48:51], v[6:7] nt
	v_lshl_add_u64 v[4:5], v[4:5], 0, s[72:73]
	v_lshl_add_u64 v[6:7], v[6:7], 0, s[72:73]
	flat_load_dwordx4 v[52:55], v[4:5] nt
	flat_load_dwordx4 v[40:43], v[6:7] nt
	v_lshl_add_u64 v[4:5], v[4:5], 0, s[72:73]
	v_lshl_add_u64 v[6:7], v[6:7], 0, s[72:73]
	flat_load_dwordx4 v[44:47], v[4:5] nt
	flat_load_dwordx4 v[32:35], v[6:7] nt
	v_lshl_add_u64 v[4:5], v[4:5], 0, s[72:73]
	v_lshl_add_u64 v[6:7], v[6:7], 0, s[72:73]
	flat_load_dwordx4 v[36:39], v[4:5] nt
	flat_load_dwordx4 v[24:27], v[6:7] nt
	v_lshl_add_u64 v[4:5], v[4:5], 0, s[72:73]
	v_lshl_add_u64 v[6:7], v[6:7], 0, s[72:73]
	flat_load_dwordx4 v[28:31], v[4:5] nt
	flat_load_dwordx4 v[16:19], v[6:7] nt
	v_lshl_add_u64 v[4:5], v[4:5], 0, s[72:73]
	v_lshl_add_u64 v[6:7], v[6:7], 0, s[72:73]
	flat_load_dwordx4 v[20:23], v[4:5] nt
	flat_load_dwordx4 v[8:11], v[6:7] nt
	v_lshl_add_u64 v[134:135], v[4:5], 0, s[72:73]
	v_lshl_add_u64 v[156:157], v[6:7], 0, s[72:73]
	flat_load_dwordx4 v[12:15], v[134:135] nt
	flat_load_dwordx4 v[4:7], v[156:157] nt
	s_lshl_b64 s[6:7], s[20:21], 17
	s_add_u32 s5, s56, s6
	s_addc_u32 s14, s57, s7
	s_lshl_b64 s[8:9], s[10:11], 13
	s_add_u32 s5, s5, s8
	s_addc_u32 s10, s14, s9
	s_add_u32 s6, s52, s6
	s_addc_u32 s7, s53, s7
	s_add_u32 s6, s6, s8
	s_addc_u32 s7, s7, s9
	s_lshl_b64 s[14:15], s[20:21], 25
	s_or_b32 s14, s14, s38
	s_add_u32 s14, s14, s8
	s_addc_u32 s15, s15, s9
	s_add_u32 s8, s58, s14
	s_addc_u32 s9, s59, s15
	v_lshlrev_b32_e32 v2, 2, v132
	s_add_u32 s14, s62, s14
	s_mov_b32 s30, s76
	v_lshl_add_u64 v[132:133], v[134:135], 0, s[72:73]
	v_lshl_add_u64 v[134:135], v[156:157], 0, s[72:73]
	s_addc_u32 s15, s63, s15
	s_mov_b64 s[20:21], 0
	s_mov_b32 s76, 0x10000
	v_lshlrev_b32_e32 v2, 2, v2
	s_waitcnt lgkmcnt(0)
	s_setprio 2
	s_nop 0
	s_nop 0
	s_nop 0
	s_nop 0
	s_nop 0
	s_nop 0
	s_nop 0
	s_nop 0
	s_nop 0
	s_nop 0
	s_nop 0
	s_nop 0
	s_nop 0
	s_nop 0
	s_nop 0
	s_barrier
	s_branch .LBB0_372
